# pipelined attention v13: MFMA block fully interleaved (one LDS read / staging write / prefetch load per MFMA gap), all addresses precomputed in the softmax block, staging unconditional
# speedup vs baseline: 1.0225x; 1.0225x over previous
.Lpipe_nost_p:
	s_add_i32 s14, s12, 0x43
	s_cmp_ge_i32 s14, s6
	s_cbranch_scc1 .Lpipe_nopf_p
	v_lshl_add_u64 v[184:185], v[144:145], 0, s[92:93]
	global_load_dwordx4 v[116:119], v[144:145], off
	global_load_dwordx4 v[120:123], v[184:185], off
	global_load_dwordx4 v[124:127], v[142:143], off
	v_add_co_u32_e32 v238, vcc, 0x80000, v142
	s_nop 1
	v_addc_co_u32_e32 v239, vcc, 0, v143, vcc
	global_load_dwordx4 v[128:131], v[238:239], off

; #define MFMA32(a, b, c) __builtin_amdgcn_mfma_f32_32x32x16_bf16((a), (b), (c), 0, 0, 0)
; DI void attn_s(const unsigned char* sK, int tt, int qb, int qs, int sub, int l31, int h,
;                const bf16x8 (&qf)[4], f32x16 (&O)[4], float& m, float& l, bf16x8 (&pb)[4]) {
;     ...
;         const unsigned char* kb = sK + l31 * A_KROWB + (sub * 64 + 8 * h) * 2;
;         bf16x8 ka[4], kc[4];
; #pragma unroll
;         for (int i = 0; i < 4; ++i) ka[i] = *(const bf16x8*)(kb + (i & 1) * 32 * A_KROWB + (i >> 1) * 32);
;         __builtin_amdgcn_sched_barrier(0);
; #pragma unroll
;         for (int i = 0; i < 4; ++i) kc[i] = *(const bf16x8*)(kb + (i & 1) * 32 * A_KROWB + (2 + (i >> 1)) * 32);
;         __builtin_amdgcn_sched_barrier(0);
; #pragma unroll
;         for (int i = 0; i < 4; ++i) st[i & 1] = MFMA32(ka[i], qf[i >> 1], st[i & 1]);
;         __builtin_amdgcn_sched_barrier(0);
; #pragma unroll
;         for (int i = 0; i < 4; ++i) st[i & 1] = MFMA32(kc[i], qf[2 + (i >> 1)], st[i & 1]);
; DI void attn_pv(const unsigned char* sV, int l31, int h, const bf16x8 (&pb)[4], f32x16 (&O)[4]) {
;     ...
;         for (int d = 0; d < 4; ++d) O[d] = MFMA32(va[d], pb[0], O[d]);
;         __builtin_amdgcn_sched_barrier(0);
; #pragma unroll
;         for (int d = 0; d < 4; ++d) va[d] = *(const bf16x8*)(vb + d * 32 * A_VROWB + 64);
;         __builtin_amdgcn_sched_barrier(0);
; #pragma unroll
;         for (int d = 0; d < 4; ++d) O[d] = MFMA32(vc[d], pb[1], O[d]);
;         __builtin_amdgcn_sched_barrier(0);
; #pragma unroll
;         for (int d = 0; d < 4; ++d) vc[d] = *(const bf16x8*)(vb + d * 32 * A_VROWB + 96);
;         __builtin_amdgcn_sched_barrier(0);
; #pragma unroll
;         for (int d = 0; d < 4; ++d) O[d] = MFMA32(va[d], pb[2], O[d]);
;         __builtin_amdgcn_sched_barrier(0);
; #pragma unroll
;         for (int d = 0; d < 4; ++d) O[d] = MFMA32(vc[d], pb[3], O[d]);
.Lpipe_norescale_l:
	v_exp_f32_e32 v66, v66
	v_exp_f32_e32 v67, v67
	v_exp_f32_e32 v68, v68
	v_exp_f32_e32 v69, v69
	v_exp_f32_e32 v70, v70
	v_exp_f32_e32 v71, v71
	v_exp_f32_e32 v72, v72
	v_exp_f32_e32 v73, v73
	v_exp_f32_e32 v74, v74
	v_exp_f32_e32 v75, v75
	v_exp_f32_e32 v76, v76
	v_exp_f32_e32 v77, v77
	v_exp_f32_e32 v78, v78
	v_exp_f32_e32 v79, v79
	v_exp_f32_e32 v80, v80
	v_exp_f32_e32 v81, v81
	v_cvt_pk_bf16_f32 v216, v82, v83
	v_cvt_pk_bf16_f32 v217, v84, v85
	v_cvt_pk_bf16_f32 v218, v86, v87
	v_cvt_pk_bf16_f32 v219, v88, v89
	v_cvt_pk_bf16_f32 v220, v90, v91
	v_cvt_pk_bf16_f32 v221, v92, v93
	v_cvt_pk_bf16_f32 v222, v94, v95
	v_cvt_pk_bf16_f32 v223, v96, v97
	v_cvt_pk_bf16_f32 v224, v66, v67
	v_cvt_pk_bf16_f32 v225, v68, v69
	v_cvt_pk_bf16_f32 v226, v70, v71
	v_cvt_pk_bf16_f32 v227, v72, v73
	v_cvt_pk_bf16_f32 v228, v74, v75
	v_cvt_pk_bf16_f32 v229, v76, v77
	v_cvt_pk_bf16_f32 v230, v78, v79
	v_cvt_pk_bf16_f32 v231, v80, v81
	v_pk_add_f32 v[68:69], v[84:85], v[68:69]
	v_pk_add_f32 v[66:67], v[82:83], v[66:67]
	v_pk_add_f32 v[72:73], v[88:89], v[72:73]
	v_pk_add_f32 v[70:71], v[86:87], v[70:71]
	v_add_f32_e32 v66, v66, v67
	v_add_f32_e32 v67, v68, v69
	v_add_f32_e32 v66, v66, v67
	v_add_f32_e32 v67, v70, v71
	v_add_f32_e32 v68, v72, v73
	v_pk_add_f32 v[76:77], v[92:93], v[76:77]
	v_pk_add_f32 v[74:75], v[90:91], v[74:75]
	v_add_f32_e32 v67, v67, v68
	v_pk_add_f32 v[80:81], v[96:97], v[80:81]
	v_pk_add_f32 v[78:79], v[94:95], v[78:79]
	v_add_f32_e32 v66, v66, v67
	v_add_f32_e32 v67, v74, v75
	v_add_f32_e32 v68, v76, v77
	v_add_f32_e32 v67, v67, v68
	v_add_f32_e32 v68, v78, v79
	v_add_f32_e32 v69, v80, v81
	v_add_f32_e32 v68, v68, v69
	v_add_f32_e32 v67, v67, v68
	v_add_f32_e32 v66, v66, v67
	v_add_f32_e32 v1, v1, v66
	v_add_u32_e32 v158, 64, v158
	v_lshl_add_u64 v[144:145], v[144:145], 0, s[90:91]
	v_lshl_add_u64 v[142:143], v[142:143], 0, s[88:89]
	v_lshl_add_u64 v[184:185], v[144:145], 0, s[92:93]
	v_add_co_u32_e32 v238, vcc, 0x80000, v142
	s_mul_i32 s98, s7, 0x8c00
	s_nop 0
	v_addc_co_u32_e32 v239, vcc, 0, v143, vcc
	v_add3_u32 v237, s98, v155, v154
	s_add_i32 s4, s7, 1
	s_cmp_lg_u32 s7, 2
	s_cselect_b32 s4, s4, 0
	s_mul_i32 s4, s4, 0x8c00
	v_add3_u32 v232, s4, v140, v139
	v_add3_u32 v233, s4, v140, v141
	v_add3_u32 v234, s4, v150, v151
	v_add_u32_e32 v235, v234, v153
	v_add_u32_e32 v234, v234, v152
	v_add_u32_e32 v235, 0x4000, v235
	v_add_u32_e32 v234, 0x4000, v234
	s_mov_b32 s13, s7
	s_add_i32 s4, s7, 1
	s_cmp_lg_u32 s7, 2
	s_cselect_b32 s7, s4, 0
	s_add_i32 s12, s12, 1
	s_cmp_eq_u32 s11, s12
	s_cbranch_scc1 .Lpipe_final
	s_barrier
	s_setprio 1
	ds_read_b128 v[160:163], v237
	ds_read_b128 v[164:167], v237 offset:32
	ds_read_b128 v[168:171], v237 offset:8704
	ds_read_b128 v[196:199], v237 offset:8736
	s_waitcnt lgkmcnt(11)
	v_mfma_f32_32x32x16_bf16 v[50:65], v[172:175], v[216:219], v[50:65]
	ds_read_b128 v[172:175], v237 offset:64
	s_waitcnt lgkmcnt(11)
	v_mfma_f32_32x32x16_bf16 v[34:49], v[176:179], v[216:219], v[34:49]
	ds_read_b128 v[176:179], v237 offset:96
	s_waitcnt lgkmcnt(11)
	v_mfma_f32_32x32x16_bf16 v[18:33], v[180:183], v[216:219], v[18:33]
	ds_read_b128 v[180:183], v237 offset:8768
	s_waitcnt lgkmcnt(11)
	v_mfma_f32_32x32x16_bf16 v[2:17], v[192:195], v[216:219], v[2:17]
	ds_read_b128 v[192:195], v237 offset:8800
	s_waitcnt lgkmcnt(11)
	v_mfma_f32_32x32x16_bf16 v[50:65], v[200:203], v[220:223], v[50:65]
	ds_read_b128 v[200:203], v191 offset:17472
	s_waitcnt lgkmcnt(11)
	v_mfma_f32_32x32x16_bf16 v[34:49], v[204:207], v[220:223], v[34:49]
	ds_read_b128 v[204:207], v191 offset:22080
	s_waitcnt lgkmcnt(11)
	v_mfma_f32_32x32x16_bf16 v[18:33], v[208:211], v[220:223], v[18:33]
	ds_read_b128 v[208:211], v191 offset:26688
	s_waitcnt lgkmcnt(11)
	v_mfma_f32_32x32x16_bf16 v[2:17], v[212:215], v[220:223], v[2:17]
	ds_read_b128 v[212:215], v191 offset:31296
	s_waitcnt lgkmcnt(11)
	v_mfma_f32_32x32x16_bf16 v[82:97], v[160:163], v[100:103], v[240:255]
	ds_read_b128 v[160:163], v191 offset:17504
	s_waitcnt lgkmcnt(10)
	v_mfma_f32_32x32x16_bf16 v[66:81], v[168:171], v[100:103], v[240:255]
	ds_read_b128 v[168:171], v191 offset:26720
	v_mfma_f32_32x32x16_bf16 v[82:97], v[164:167], v[104:107], v[82:97]
	ds_read_b128 v[164:167], v191 offset:22112
	s_waitcnt lgkmcnt(11)
	v_mfma_f32_32x32x16_bf16 v[66:81], v[196:199], v[104:107], v[66:81]
	ds_read_b128 v[196:199], v191 offset:31328
	s_waitcnt lgkmcnt(11)
	v_mfma_f32_32x32x16_bf16 v[82:97], v[172:175], v[108:111], v[82:97]
	s_waitcnt vmcnt(3)
	ds_write_b128 v232, v[116:119]
	s_waitcnt lgkmcnt(10)
	v_mfma_f32_32x32x16_bf16 v[66:81], v[180:183], v[108:111], v[66:81]
	s_waitcnt vmcnt(2)
	ds_write_b128 v233, v[120:123]
	v_mfma_f32_32x32x16_bf16 v[82:97], v[176:179], v[112:115], v[82:97]
	s_waitcnt vmcnt(1)
	ds_write2_b64 v234, v[124:125], v[126:127] offset0:128 offset1:130
	s_waitcnt lgkmcnt(11)
	v_mfma_f32_32x32x16_bf16 v[66:81], v[192:195], v[112:115], v[66:81]
	s_waitcnt vmcnt(0)
	ds_write2_b64 v235, v[128:129], v[130:131] offset0:128 offset1:130
	s_add_i32 s14, s12, 0x43
	s_cmp_ge_i32 s14, s6
	s_cbranch_scc1 .Lpipe_k2_nopf
	s_waitcnt lgkmcnt(11)
	v_mfma_f32_32x32x16_bf16 v[50:65], v[200:203], v[224:227], v[50:65]
	global_load_dwordx4 v[116:119], v[144:145], off
	s_waitcnt lgkmcnt(10)
	v_mfma_f32_32x32x16_bf16 v[34:49], v[204:207], v[224:227], v[34:49]
	global_load_dwordx4 v[120:123], v[184:185], off
	s_waitcnt lgkmcnt(9)
	v_mfma_f32_32x32x16_bf16 v[18:33], v[208:211], v[224:227], v[18:33]
	global_load_dwordx4 v[124:127], v[142:143], off
	s_waitcnt lgkmcnt(8)
	v_mfma_f32_32x32x16_bf16 v[2:17], v[212:215], v[224:227], v[2:17]
	global_load_dwordx4 v[128:131], v[238:239], off
	s_branch .Lpipe_k3
.Lpipe_k2_nopf:
	s_waitcnt lgkmcnt(11)
	v_mfma_f32_32x32x16_bf16 v[50:65], v[200:203], v[224:227], v[50:65]
	s_waitcnt lgkmcnt(10)
	v_mfma_f32_32x32x16_bf16 v[34:49], v[204:207], v[224:227], v[34:49]
	s_waitcnt lgkmcnt(9)
	v_mfma_f32_32x32x16_bf16 v[18:33], v[208:211], v[224:227], v[18:33]
	s_waitcnt lgkmcnt(8)
	v_mfma_f32_32x32x16_bf16 v[2:17], v[212:215], v[224:227], v[2:17]
.Lpipe_k3:
	s_waitcnt lgkmcnt(7)
	v_mfma_f32_32x32x16_bf16 v[50:65], v[160:163], v[228:231], v[50:65]
	s_waitcnt lgkmcnt(5)
	v_mfma_f32_32x32x16_bf16 v[34:49], v[164:167], v[228:231], v[34:49]
	v_mfma_f32_32x32x16_bf16 v[18:33], v[168:171], v[228:231], v[18:33]
	s_waitcnt lgkmcnt(4)
	v_mfma_f32_32x32x16_bf16 v[2:17], v[196:199], v[228:231], v[2:17]
	s_setprio 0
	s_waitcnt lgkmcnt(0)
	s_barrier
	s_branch .Lpipe_loop
